# phase 0 row loop: next row's four loads issued one iteration ahead (counted vmcnt(7) at the loop top leaves the previous stores in flight), on top of the straight-line p conversion
# speedup vs baseline: 1.0042x; 1.0017x over previous
.LBB0_58:
	s_or_b64 exec, exec, s[14:15]
	v_lshl_add_u64 v[72:73], v[72:73], 0, s[2:3]
	v_cmp_lt_i32_e32 vcc, s18, v72
	v_lshl_add_u64 v[138:139], v[138:139], 0, s[6:7]
	v_lshl_add_u64 v[140:141], v[140:141], 0, s[8:9]
	s_or_b64 s[12:13], vcc, s[12:13]
	v_lshl_add_u64 v[142:143], v[142:143], 0, s[10:11]
	s_andn2_b64 exec, exec, s[12:13]
	s_cbranch_execz .LBB0_61
.LBB0_59:
	s_waitcnt vmcnt(7)
.Lp0_top:
	v_readlane_b32 s56, v237, 3
	v_readlane_b32 s57, v237, 4
	v_readlane_b32 s59, v237, 6
	v_readlane_b32 s58, v237, 5
	v_mov_b32_e32 v146, v200
	v_mov_b32_e32 v147, v201
	v_mov_b32_e32 v148, v202
	v_mov_b32_e32 v149, v203
	v_mov_b32_e32 v150, v204
	v_mov_b32_e32 v151, v205
	v_mov_b32_e32 v152, v206
	v_mov_b32_e32 v153, v207
	v_mov_b32_e32 v154, v208
	v_mov_b32_e32 v155, v209
	v_mov_b32_e32 v156, v210
	v_mov_b32_e32 v157, v211
	v_mov_b32_e32 v188, v212
	v_mov_b32_e32 v189, v213
	v_mov_b32_e32 v190, v214
	v_mov_b32_e32 v191, v215
	v_add_u32_e32 v222, s2, v72
	v_cmp_lt_i32_e32 vcc, s18, v222
	s_and_b64 vcc, exec, vcc
	s_cbranch_vccnz .Lp0_nopf
	v_add_u32_e32 v218, 0xffffc000, v222
	v_cmp_gt_i32_e32 vcc, s16, v222
	v_mov_b32_e32 v220, s59
	v_mov_b32_e32 v221, s57
	v_mov_b32_e32 v219, 0
	v_cndmask_b32_e32 v218, v218, v222, vcc
	v_cndmask_b32_e32 v221, v220, v221, vcc
	v_mov_b32_e32 v220, s58
	v_mov_b32_e32 v223, s56
	v_cndmask_b32_e32 v220, v220, v223, vcc
	v_lshlrev_b64 v[218:219], 12, v[218:219]
	v_lshl_add_u64 v[218:219], v[220:221], 0, v[218:219]
	v_lshl_add_u64 v[218:219], v[218:219], 0, v[70:71]
	global_load_dwordx4 v[200:203], v[218:219], off
	global_load_dwordx4 v[204:207], v[218:219], off offset:1024
	global_load_dwordx4 v[208:211], v[218:219], off offset:2048
	global_load_dwordx4 v[212:215], v[218:219], off offset:3072
.Lp0_nopf:
	v_lshl_add_u64 v[144:145], s[54:55], 0, v[142:143]
	v_readlane_b32 s60, v237, 7
	v_readlane_b32 s61, v237, 8
	v_readlane_b32 s62, v237, 9
	v_readlane_b32 s63, v237, 10
	v_readlane_b32 s64, v237, 11
	v_readlane_b32 s65, v237, 12
	v_readlane_b32 s66, v237, 13
	v_readlane_b32 s67, v237, 14
	v_readlane_b32 s68, v237, 15
	v_readlane_b32 s69, v237, 16
	v_readlane_b32 s70, v237, 17
	v_readlane_b32 s71, v237, 18
	v_cvt_pk_bf16_f32 v68, v146, v147
	v_cvt_pk_bf16_f32 v69, v148, v149
	global_store_dwordx2 v[144:145], v[68:69], off
	s_waitcnt lgkmcnt(0)
	v_pk_mul_f32 v[172:173], v[146:147], v[134:135]
	v_pk_mul_f32 v[174:175], v[146:147], v[122:123]
	v_pk_mul_f32 v[180:181], v[146:147], v[110:111]
	v_pk_mul_f32 v[158:159], v[146:147], v[146:147]
	v_pk_mul_f32 v[182:183], v[146:147], v[98:99]
	v_pk_fma_f32 v[172:173], v[146:147], v[6:7], v[172:173] op_sel:[1,0,0] op_sel_hi:[0,1,1]
	v_pk_fma_f32 v[174:175], v[146:147], v[14:15], v[174:175] op_sel:[1,0,0] op_sel_hi:[0,1,1]
	v_pk_fma_f32 v[180:181], v[146:147], v[22:23], v[180:181] op_sel:[1,0,0] op_sel_hi:[0,1,1]
	v_pk_mul_f32 v[160:161], v[148:149], v[148:149]
	v_mov_b32_e32 v170, v149
	v_pk_fma_f32 v[146:147], v[146:147], v[30:31], v[182:183] op_sel:[1,0,0] op_sel_hi:[0,1,1]
	v_add_f32_e32 v169, v158, v159
	v_pk_fma_f32 v[158:159], v[148:149], v[136:137], v[172:173] op_sel_hi:[0,1,1]
	v_pk_fma_f32 v[172:173], v[148:149], v[124:125], v[174:175] op_sel_hi:[0,1,1]
	v_pk_fma_f32 v[174:175], v[148:149], v[112:113], v[180:181] op_sel_hi:[0,1,1]
	v_pk_fma_f32 v[146:147], v[148:149], v[100:101], v[146:147] op_sel_hi:[0,1,1]
	v_add_f32_e32 v160, v169, v160
	v_pk_fma_f32 v[148:149], v[170:171], v[8:9], v[158:159] op_sel_hi:[0,1,1]
	v_pk_fma_f32 v[158:159], v[170:171], v[16:17], v[172:173] op_sel_hi:[0,1,1]
	v_pk_fma_f32 v[172:173], v[170:171], v[24:25], v[174:175] op_sel_hi:[0,1,1]
	v_add_f32_e32 v169, v160, v161
	v_pk_add_f32 v[160:161], v[172:173], 0 op_sel_hi:[1,0]
	v_pk_fma_f32 v[146:147], v[170:171], v[32:33], v[146:147] op_sel_hi:[0,1,1]
	v_pk_add_f32 v[148:149], v[148:149], 0 op_sel_hi:[1,0]
	v_pk_add_f32 v[158:159], v[158:159], 0 op_sel_hi:[1,0]
	v_pk_add_f32 v[146:147], v[146:147], 0 op_sel_hi:[1,0]
	v_cvt_pk_bf16_f32 v68, v150, v151
	v_cvt_pk_bf16_f32 v69, v152, v153
	global_store_dwordx2 v[144:145], v[68:69], off offset:512
	v_pk_mul_f32 v[172:173], v[150:151], v[150:151]
	v_pk_mul_f32 v[180:181], v[150:151], v[132:133]
	v_pk_mul_f32 v[182:183], v[150:151], v[120:121]
	v_pk_mul_f32 v[184:185], v[150:151], v[108:109]
	v_pk_mul_f32 v[186:187], v[150:151], v[96:97]
	v_pk_mul_f32 v[174:175], v[152:153], v[152:153]
	v_pk_fma_f32 v[180:181], v[150:151], v[2:3], v[180:181] op_sel:[1,0,0] op_sel_hi:[0,1,1]
	v_pk_fma_f32 v[182:183], v[150:151], v[10:11], v[182:183] op_sel:[1,0,0] op_sel_hi:[0,1,1]
	v_pk_fma_f32 v[184:185], v[150:151], v[18:19], v[184:185] op_sel:[1,0,0] op_sel_hi:[0,1,1]
	v_pk_fma_f32 v[150:151], v[150:151], v[26:27], v[186:187] op_sel:[1,0,0] op_sel_hi:[0,1,1]
	v_add_f32_e32 v177, v172, v173
	v_mov_b32_e32 v170, v153
	v_pk_fma_f32 v[172:173], v[152:153], v[4:5], v[180:181] op_sel_hi:[0,1,1]
	v_pk_fma_f32 v[180:181], v[152:153], v[12:13], v[182:183] op_sel_hi:[0,1,1]
	v_pk_fma_f32 v[182:183], v[152:153], v[20:21], v[184:185] op_sel_hi:[0,1,1]
	v_pk_fma_f32 v[150:151], v[152:153], v[28:29], v[150:151] op_sel_hi:[0,1,1]
	v_add_f32_e32 v152, v177, v174
	v_add_f32_e32 v177, v152, v175
	v_pk_fma_f32 v[152:153], v[170:171], v[130:131], v[172:173] op_sel_hi:[0,1,1]
	v_pk_fma_f32 v[172:173], v[170:171], v[118:119], v[180:181] op_sel_hi:[0,1,1]
	v_pk_fma_f32 v[174:175], v[170:171], v[106:107], v[182:183] op_sel_hi:[0,1,1]
	v_pk_fma_f32 v[150:151], v[170:171], v[94:95], v[150:151] op_sel_hi:[0,1,1]
	v_pk_add_f32 v[148:149], v[148:149], v[152:153]
	v_pk_add_f32 v[152:153], v[158:159], v[172:173]
	v_pk_add_f32 v[158:159], v[160:161], v[174:175]
	v_pk_add_f32 v[146:147], v[146:147], v[150:151]
	v_add_f32_e32 v169, v169, v177
	v_cvt_pk_bf16_f32 v68, v154, v155
	v_cvt_pk_bf16_f32 v69, v156, v157
	global_store_dwordx2 v[144:145], v[68:69], off offset:1024
	v_pk_mul_f32 v[150:151], v[154:155], v[154:155]
	v_pk_mul_f32 v[172:173], v[154:155], v[128:129]
	v_pk_mul_f32 v[174:175], v[154:155], v[116:117]
	v_pk_mul_f32 v[180:181], v[154:155], v[104:105]
	v_pk_mul_f32 v[182:183], v[154:155], v[92:93]
	v_pk_mul_f32 v[160:161], v[156:157], v[156:157]
	v_pk_fma_f32 v[172:173], v[154:155], v[34:35], v[172:173] op_sel:[1,0,0] op_sel_hi:[0,1,1]
	v_pk_fma_f32 v[174:175], v[154:155], v[42:43], v[174:175] op_sel:[1,0,0] op_sel_hi:[0,1,1]
	v_pk_fma_f32 v[180:181], v[154:155], v[50:51], v[180:181] op_sel:[1,0,0] op_sel_hi:[0,1,1]
	v_pk_fma_f32 v[154:155], v[154:155], v[58:59], v[182:183] op_sel:[1,0,0] op_sel_hi:[0,1,1]
	v_add_f32_e32 v150, v150, v151
	v_mov_b32_e32 v170, v157
	v_add_f32_e32 v160, v150, v160
	v_pk_fma_f32 v[150:151], v[156:157], v[36:37], v[172:173] op_sel_hi:[0,1,1]
	v_pk_fma_f32 v[172:173], v[156:157], v[44:45], v[174:175] op_sel_hi:[0,1,1]
	v_pk_fma_f32 v[174:175], v[156:157], v[52:53], v[180:181] op_sel_hi:[0,1,1]
	v_pk_fma_f32 v[154:155], v[156:157], v[60:61], v[154:155] op_sel_hi:[0,1,1]
	v_add_f32_e32 v177, v160, v161
	v_pk_fma_f32 v[150:151], v[170:171], v[74:75], v[150:151] op_sel_hi:[0,1,1]
	v_pk_fma_f32 v[156:157], v[170:171], v[78:79], v[172:173] op_sel_hi:[0,1,1]
	v_pk_fma_f32 v[160:161], v[170:171], v[82:83], v[174:175] op_sel_hi:[0,1,1]
	v_pk_fma_f32 v[154:155], v[170:171], v[86:87], v[154:155] op_sel_hi:[0,1,1]
	v_pk_add_f32 v[148:149], v[148:149], v[150:151]
	v_pk_add_f32 v[150:151], v[152:153], v[156:157]
	v_pk_add_f32 v[152:153], v[158:159], v[160:161]
	v_pk_add_f32 v[146:147], v[146:147], v[154:155]
	v_add_f32_e32 v169, v169, v177
	v_pk_mul_f32 v[154:155], v[188:189], v[188:189]
	v_pk_mul_f32 v[158:159], v[188:189], v[38:39]
	v_pk_mul_f32 v[160:161], v[188:189], v[46:47]
	v_pk_mul_f32 v[172:173], v[188:189], v[54:55]
	v_pk_mul_f32 v[174:175], v[188:189], v[62:63]
	v_pk_mul_f32 v[156:157], v[190:191], v[190:191]
	v_add_f32_e32 v177, v154, v155
	v_pk_fma_f32 v[154:155], v[188:189], v[126:127], v[158:159] op_sel:[0,0,1] op_sel_hi:[1,1,0]
	v_pk_fma_f32 v[158:159], v[188:189], v[114:115], v[160:161] op_sel:[0,0,1] op_sel_hi:[1,1,0]
	v_pk_fma_f32 v[160:161], v[188:189], v[102:103], v[172:173] op_sel:[0,0,1] op_sel_hi:[1,1,0]
	v_pk_fma_f32 v[172:173], v[188:189], v[90:91], v[174:175] op_sel:[0,0,1] op_sel_hi:[1,1,0]
	v_mov_b32_e32 v170, v191
	v_add_f32_e32 v156, v177, v156
	v_pk_fma_f32 v[154:155], v[190:191], v[76:77], v[154:155] op_sel_hi:[0,1,1]
	v_pk_fma_f32 v[158:159], v[190:191], v[80:81], v[158:159] op_sel_hi:[0,1,1]
	v_pk_fma_f32 v[160:161], v[190:191], v[84:85], v[160:161] op_sel_hi:[0,1,1]
	v_pk_fma_f32 v[172:173], v[190:191], v[88:89], v[172:173] op_sel_hi:[0,1,1]
	v_add_f32_e32 v174, v156, v157
	v_pk_fma_f32 v[154:155], v[170:171], v[40:41], v[154:155] op_sel_hi:[0,1,1]
	v_pk_fma_f32 v[156:157], v[170:171], v[48:49], v[158:159] op_sel_hi:[0,1,1]
	v_pk_fma_f32 v[158:159], v[170:171], v[56:57], v[160:161] op_sel_hi:[0,1,1]
	v_pk_fma_f32 v[160:161], v[170:171], v[64:65], v[172:173] op_sel_hi:[0,1,1]
	v_add_f32_e32 v169, v169, v174
	v_pk_add_f32 v[148:149], v[148:149], v[154:155]
	v_pk_add_f32 v[150:151], v[150:151], v[156:157]
	v_pk_add_f32 v[152:153], v[152:153], v[158:159]
	v_pk_add_f32 v[146:147], v[146:147], v[160:161]
	ds_bpermute_b32 v170, v162, v169
	ds_bpermute_b32 v154, v162, v148
	ds_bpermute_b32 v155, v162, v149
	ds_bpermute_b32 v156, v162, v150
	ds_bpermute_b32 v157, v162, v151
	ds_bpermute_b32 v158, v162, v152
	ds_bpermute_b32 v159, v162, v153
	ds_bpermute_b32 v160, v162, v146
	ds_bpermute_b32 v161, v162, v147
	s_waitcnt lgkmcnt(8)
	v_add_f32_e32 v169, v169, v170
	s_waitcnt lgkmcnt(6)
	v_pk_add_f32 v[148:149], v[148:149], v[154:155]
	s_waitcnt lgkmcnt(4)
	v_pk_add_f32 v[150:151], v[150:151], v[156:157]
	s_waitcnt lgkmcnt(2)
	v_pk_add_f32 v[152:153], v[152:153], v[158:159]
	s_waitcnt lgkmcnt(0)
	v_pk_add_f32 v[146:147], v[146:147], v[160:161]
	ds_bpermute_b32 v170, v163, v169
	ds_bpermute_b32 v154, v163, v148
	ds_bpermute_b32 v155, v163, v149
	ds_bpermute_b32 v156, v163, v150
	ds_bpermute_b32 v157, v163, v151
	ds_bpermute_b32 v158, v163, v152
	ds_bpermute_b32 v159, v163, v153
	ds_bpermute_b32 v160, v163, v146
	ds_bpermute_b32 v161, v163, v147
	s_waitcnt lgkmcnt(8)
	v_add_f32_e32 v169, v169, v170
	s_waitcnt lgkmcnt(6)
	v_pk_add_f32 v[148:149], v[148:149], v[154:155]
	s_waitcnt lgkmcnt(4)
	v_pk_add_f32 v[150:151], v[150:151], v[156:157]
	s_waitcnt lgkmcnt(2)
	v_pk_add_f32 v[152:153], v[152:153], v[158:159]
	s_waitcnt lgkmcnt(0)
	v_pk_add_f32 v[146:147], v[146:147], v[160:161]
	ds_bpermute_b32 v170, v164, v169
	ds_bpermute_b32 v154, v164, v148
	ds_bpermute_b32 v155, v164, v149
	ds_bpermute_b32 v156, v164, v150
	ds_bpermute_b32 v157, v164, v151
	ds_bpermute_b32 v158, v164, v152
	ds_bpermute_b32 v159, v164, v153
	ds_bpermute_b32 v160, v164, v146
	ds_bpermute_b32 v161, v164, v147
	s_waitcnt lgkmcnt(8)
	v_add_f32_e32 v169, v169, v170
	s_waitcnt lgkmcnt(6)
	v_pk_add_f32 v[148:149], v[148:149], v[154:155]
	s_waitcnt lgkmcnt(4)
	v_pk_add_f32 v[150:151], v[150:151], v[156:157]
	s_waitcnt lgkmcnt(2)
	v_pk_add_f32 v[152:153], v[152:153], v[158:159]
	s_waitcnt lgkmcnt(0)
	v_pk_add_f32 v[146:147], v[146:147], v[160:161]
	ds_bpermute_b32 v170, v165, v169
	ds_bpermute_b32 v154, v165, v148
	ds_bpermute_b32 v155, v165, v149
	ds_bpermute_b32 v156, v165, v150
	ds_bpermute_b32 v157, v165, v151
	ds_bpermute_b32 v158, v165, v152
	ds_bpermute_b32 v159, v165, v153
	ds_bpermute_b32 v160, v165, v146
	ds_bpermute_b32 v161, v165, v147
	s_waitcnt lgkmcnt(8)
	v_add_f32_e32 v169, v169, v170
	s_waitcnt lgkmcnt(6)
	v_pk_add_f32 v[148:149], v[148:149], v[154:155]
	s_waitcnt lgkmcnt(4)
	v_pk_add_f32 v[150:151], v[150:151], v[156:157]
	s_waitcnt lgkmcnt(2)
	v_pk_add_f32 v[152:153], v[152:153], v[158:159]
	s_waitcnt lgkmcnt(0)
	v_pk_add_f32 v[158:159], v[146:147], v[160:161]
	ds_bpermute_b32 v156, v166, v169
	ds_bpermute_b32 v146, v166, v148
	ds_bpermute_b32 v147, v166, v149
	ds_bpermute_b32 v154, v166, v150
	ds_bpermute_b32 v155, v166, v151
	ds_bpermute_b32 v160, v166, v152
	ds_bpermute_b32 v161, v166, v153
	ds_bpermute_b32 v172, v166, v158
	ds_bpermute_b32 v173, v166, v159
	s_waitcnt lgkmcnt(8)
	v_add_f32_e32 v169, v169, v156
	s_waitcnt lgkmcnt(6)
	v_pk_add_f32 v[156:157], v[148:149], v[146:147]
	s_waitcnt lgkmcnt(4)
	v_pk_add_f32 v[154:155], v[150:151], v[154:155]
	s_waitcnt lgkmcnt(2)
	v_pk_add_f32 v[146:147], v[152:153], v[160:161]
	s_waitcnt lgkmcnt(0)
	v_pk_add_f32 v[148:149], v[158:159], v[172:173]
	ds_bpermute_b32 v170, v167, v169
	ds_bpermute_b32 v160, v167, v156
	ds_bpermute_b32 v161, v167, v157
	ds_bpermute_b32 v158, v167, v154
	ds_bpermute_b32 v159, v167, v155
	ds_bpermute_b32 v150, v167, v146
	ds_bpermute_b32 v151, v167, v147
	ds_bpermute_b32 v152, v167, v148
	ds_bpermute_b32 v153, v167, v149
	v_cvt_pk_bf16_f32 v66, v188, v189
	v_cvt_pk_bf16_f32 v67, v190, v191
	global_store_dwordx2 v[144:145], v[66:67], off offset:1536
	s_and_saveexec_b64 s[14:15], s[4:5]
	s_cbranch_execz .LBB0_58
	s_waitcnt lgkmcnt(8)
	v_add_f32_e32 v66, v169, v170
	v_fmamk_f32 v66, v66, 0x3a800000, v168
	v_mul_f32_e32 v67, 0x4b800000, v66
	v_cmp_gt_f32_e32 vcc, s17, v66
	v_lshl_add_u64 v[144:145], s[54:55], 0, v[140:141]
	s_nop 0
	v_cndmask_b32_e32 v66, v66, v67, vcc
	v_rsq_f32_e32 v68, v66
	v_lshl_add_u64 v[66:67], s[54:55], 0, v[138:139]
	v_mul_f32_e32 v69, 0x45800000, v68
	v_cndmask_b32_e32 v170, v68, v69, vcc
	global_store_dword v[66:67], v170, off
	s_waitcnt lgkmcnt(6)
	v_pk_add_f32 v[66:67], v[156:157], v[160:161]
	s_waitcnt lgkmcnt(4)
	v_pk_add_f32 v[68:69], v[154:155], v[158:159]
	v_add_co_u32_e32 v144, vcc, 0xf291000, v144
	v_pk_mul_f32 v[66:67], v[66:67], v[170:171] op_sel_hi:[1,0]
	v_pk_mul_f32 v[68:69], v[170:171], v[68:69] op_sel_hi:[0,1]
	v_addc_co_u32_e32 v145, vcc, 0, v145, vcc
	global_store_dwordx4 v[144:145], v[66:69], off
	s_waitcnt lgkmcnt(2)
	s_nop 0
	v_pk_add_f32 v[66:67], v[146:147], v[150:151]
	s_waitcnt lgkmcnt(0)
	v_pk_add_f32 v[68:69], v[148:149], v[152:153]
	v_pk_mul_f32 v[66:67], v[170:171], v[66:67] op_sel_hi:[0,1]
	v_pk_mul_f32 v[68:69], v[170:171], v[68:69] op_sel_hi:[0,1]
	global_store_dwordx4 v[144:145], v[66:69], off offset:16
	s_branch .LBB0_58
.Lp0_pro:
	v_readlane_b32 s56, v237, 3
	v_readlane_b32 s57, v237, 4
	v_readlane_b32 s59, v237, 6
	v_readlane_b32 s58, v237, 5
	v_add_u32_e32 v218, 0xffffc000, v72
	v_cmp_gt_i32_e32 vcc, s16, v72
	v_mov_b32_e32 v220, s59
	v_mov_b32_e32 v221, s57
	v_mov_b32_e32 v219, 0
	v_cndmask_b32_e32 v218, v218, v72, vcc
	v_cndmask_b32_e32 v221, v220, v221, vcc
	v_mov_b32_e32 v220, s58
	v_mov_b32_e32 v223, s56
	v_cndmask_b32_e32 v220, v220, v223, vcc
	v_lshlrev_b64 v[218:219], 12, v[218:219]
	v_lshl_add_u64 v[218:219], v[220:221], 0, v[218:219]
	v_lshl_add_u64 v[218:219], v[218:219], 0, v[70:71]
	global_load_dwordx4 v[200:203], v[218:219], off
	global_load_dwordx4 v[204:207], v[218:219], off offset:1024
	global_load_dwordx4 v[208:211], v[218:219], off offset:2048
	global_load_dwordx4 v[212:215], v[218:219], off offset:3072
	s_waitcnt vmcnt(0)
	s_branch .Lp0_top
